# retention output phase: group-norm gate waits count the next unit's prefetch behind them (no stall on the prefetch's first load); last unit drains its gate loads first
# baseline (speedup 1.0000x reference)
.LBB0_637:
	v_lshl_add_u32 v4, v161, 2, 0
	v_add_u32_e32 v0, s58, v4
	ds_read_b128 v[0:3], v0
	s_lshl_b64 s[2:3], s[20:21], 12
	s_add_u32 s6, s68, s2
	s_addc_u32 s7, s69, s3
	s_waitcnt lgkmcnt(0)
	v_mov_b32_e32 v6, v1
	v_mov_b32_e32 v7, v2
	v_mov_b32_e32 v8, v0
	v_mov_b32_e32 v9, v3
	v_pk_add_f32 v[6:7], v[6:7], v[8:9]
	s_nop 0
	v_add_f32_e32 v5, v6, v7
	s_nop 1
	v_add_f32_dpp v5, v5, v5 quad_perm:[1,0,3,2] row_mask:0xf bank_mask:0xf
	s_nop 1
	v_add_f32_dpp v5, v5, v5 quad_perm:[2,3,0,1] row_mask:0xf bank_mask:0xf
	s_nop 1
	v_add_f32_dpp v5, v5, v5 row_half_mirror row_mask:0xf bank_mask:0xf
	s_nop 1
	v_add_f32_dpp v5, v5, v5 row_mirror row_mask:0xf bank_mask:0xf
	v_mov_b32_e32 v6, v5
	s_nop 1
	v_permlane16_swap_b32_e32 v5, v6
	v_add_f32_e32 v5, v5, v6
	v_mov_b32_e32 v6, v5
	s_nop 1
	v_permlane32_swap_b32_e32 v5, v6
	v_add_f32_e32 v5, v5, v6
	v_fmamk_f32 v1, v5, 0xbb800000, v1
	v_fmamk_f32 v0, v5, 0xbb800000, v0
	v_fmamk_f32 v3, v5, 0xbb800000, v3
	v_fmac_f32_e32 v2, 0xbb800000, v5
	v_pk_mul_f32 v[6:7], v[2:3], v[2:3]
	v_pk_mul_f32 v[8:9], v[0:1], v[0:1]
	s_nop 0
	v_pk_mov_b32 v[10:11], v[8:9], v[6:7] op_sel:[1,0]
	v_mov_b32_e32 v9, v7
	v_pk_add_f32 v[6:7], v[10:11], v[8:9]
	s_nop 0
	v_add_f32_e32 v5, v6, v7
	s_nop 1
	v_add_f32_dpp v5, v5, v5 quad_perm:[1,0,3,2] row_mask:0xf bank_mask:0xf
	s_nop 1
	v_add_f32_dpp v5, v5, v5 quad_perm:[2,3,0,1] row_mask:0xf bank_mask:0xf
	s_nop 1
	v_add_f32_dpp v5, v5, v5 row_half_mirror row_mask:0xf bank_mask:0xf
	s_nop 1
	v_add_f32_dpp v5, v5, v5 row_mirror row_mask:0xf bank_mask:0xf
	v_mov_b32_e32 v6, v5
	s_nop 1
	v_permlane16_swap_b32_e32 v5, v6
	v_add_f32_e32 v5, v5, v6
	v_mov_b32_e32 v6, v5
	s_nop 1
	v_permlane32_swap_b32_e32 v5, v6
	v_add_f32_e32 v5, v5, v6
	v_fmamk_f32 v5, v5, 0x3b800000, v251
	v_cmp_gt_f32_e32 vcc, s19, v5
	v_mul_f32_e32 v6, 0x4f800000, v5
	s_nop 0
	v_cndmask_b32_e32 v5, v5, v6, vcc
	v_sqrt_f32_e32 v6, v5
	s_nop 0
	v_add_u32_e32 v7, -1, v6
	v_fma_f32 v8, -v7, v6, v5
	v_cmp_ge_f32_e64 s[2:3], 0, v8
	v_add_u32_e32 v8, 1, v6
	s_nop 0
	v_cndmask_b32_e64 v7, v6, v7, s[2:3]
	v_fma_f32 v6, -v8, v6, v5
	v_cmp_lt_f32_e64 s[2:3], 0, v6
	s_nop 1
	v_cndmask_b32_e64 v6, v7, v8, s[2:3]
	v_mul_f32_e32 v7, 0x37800000, v6
	v_cndmask_b32_e32 v6, v6, v7, vcc
	v_cmp_class_f32_e32 vcc, v5, v252
	s_nop 1
	v_cndmask_b32_e32 v5, v6, v5, vcc
	v_div_scale_f32 v6, s[2:3], v5, v5, 1.0
	v_rcp_f32_e32 v7, v6
	s_or_b32 s2, s54, s59
	v_or_b32_e32 v212, s2, v161
	v_fma_f32 v8, -v6, v7, 1.0
	v_fmac_f32_e32 v7, v8, v7
	v_div_scale_f32 v8, vcc, 1.0, v5, 1.0
	v_mul_f32_e32 v9, v8, v7
	v_fma_f32 v10, -v6, v9, v8
	v_fmac_f32_e32 v9, v10, v7
	v_fma_f32 v6, -v6, v9, v8
	v_div_fmas_f32 v6, v6, v7, v9
	v_div_fixup_f32 v6, v6, v5, 1.0
	v_pk_mul_f32 v[0:1], v[0:1], v[6:7] op_sel_hi:[1,0]
	s_waitcnt vmcnt(31)
	v_lshlrev_b32_e32 v8, 16, v158
	v_and_b32_e32 v9, 0xffff0000, v158
	v_pk_mul_f32 v[2:3], v[2:3], v[6:7] op_sel_hi:[1,0]
	v_lshlrev_b32_e32 v6, 16, v159
	v_and_b32_e32 v7, 0xffff0000, v159
	v_pk_mul_f32 v[0:1], v[0:1], v[8:9]
	v_pk_mul_f32 v[2:3], v[2:3], v[6:7]
	v_cvt_pk_bf16_f32 v0, v0, v1
	v_cvt_pk_bf16_f32 v1, v2, v3
	v_lshl_add_u64 v[2:3], v[212:213], 1, s[6:7]
	global_store_dwordx2 v[2:3], v[0:1], off
	v_add_u32_e32 v0, s60, v4
	ds_read_b128 v[0:3], v0
	s_waitcnt lgkmcnt(0)
	v_mov_b32_e32 v6, v1
	v_mov_b32_e32 v7, v2
	v_mov_b32_e32 v8, v0
	v_mov_b32_e32 v9, v3
	v_pk_add_f32 v[6:7], v[6:7], v[8:9]
	s_nop 0
	v_add_f32_e32 v5, v6, v7
	s_nop 1
	v_add_f32_dpp v5, v5, v5 quad_perm:[1,0,3,2] row_mask:0xf bank_mask:0xf
	s_nop 1
	v_add_f32_dpp v5, v5, v5 quad_perm:[2,3,0,1] row_mask:0xf bank_mask:0xf
	s_nop 1
	v_add_f32_dpp v5, v5, v5 row_half_mirror row_mask:0xf bank_mask:0xf
	s_nop 1
	v_add_f32_dpp v5, v5, v5 row_mirror row_mask:0xf bank_mask:0xf
	v_mov_b32_e32 v6, v5
	s_nop 1
	v_permlane16_swap_b32_e32 v5, v6
	v_add_f32_e32 v5, v5, v6
	v_mov_b32_e32 v6, v5
	s_nop 1
	v_permlane32_swap_b32_e32 v5, v6
	v_add_f32_e32 v5, v5, v6
	v_fmamk_f32 v1, v5, 0xbb800000, v1
	v_fmamk_f32 v0, v5, 0xbb800000, v0
	v_fmamk_f32 v3, v5, 0xbb800000, v3
	v_fmac_f32_e32 v2, 0xbb800000, v5
	v_pk_mul_f32 v[6:7], v[2:3], v[2:3]
	v_pk_mul_f32 v[8:9], v[0:1], v[0:1]
	s_nop 0
	v_pk_mov_b32 v[10:11], v[8:9], v[6:7] op_sel:[1,0]
	v_mov_b32_e32 v9, v7
	v_pk_add_f32 v[6:7], v[10:11], v[8:9]
	s_nop 0
	v_add_f32_e32 v5, v6, v7
	s_nop 1
	v_add_f32_dpp v5, v5, v5 quad_perm:[1,0,3,2] row_mask:0xf bank_mask:0xf
	s_nop 1
	v_add_f32_dpp v5, v5, v5 quad_perm:[2,3,0,1] row_mask:0xf bank_mask:0xf
	s_nop 1
	v_add_f32_dpp v5, v5, v5 row_half_mirror row_mask:0xf bank_mask:0xf
	s_nop 1
	v_add_f32_dpp v5, v5, v5 row_mirror row_mask:0xf bank_mask:0xf
	v_mov_b32_e32 v6, v5
	s_nop 1
	v_permlane16_swap_b32_e32 v5, v6
	v_add_f32_e32 v5, v5, v6
	v_mov_b32_e32 v6, v5
	s_nop 1
	v_permlane32_swap_b32_e32 v5, v6
	v_add_f32_e32 v5, v5, v6
	v_fmamk_f32 v5, v5, 0x3b800000, v251
	v_cmp_gt_f32_e32 vcc, s19, v5
	v_mul_f32_e32 v6, 0x4f800000, v5
	s_nop 0
	v_cndmask_b32_e32 v5, v5, v6, vcc
	v_sqrt_f32_e32 v6, v5
	s_nop 0
	v_add_u32_e32 v7, -1, v6
	v_fma_f32 v8, -v7, v6, v5
	v_cmp_ge_f32_e64 s[2:3], 0, v8
	v_add_u32_e32 v8, 1, v6
	s_nop 0
	v_cndmask_b32_e64 v7, v6, v7, s[2:3]
	v_fma_f32 v6, -v8, v6, v5
	v_cmp_lt_f32_e64 s[2:3], 0, v6
	s_nop 1
	v_cndmask_b32_e64 v6, v7, v8, s[2:3]
	v_mul_f32_e32 v7, 0x37800000, v6
	v_cndmask_b32_e32 v6, v6, v7, vcc
	v_cmp_class_f32_e32 vcc, v5, v252
	s_nop 1
	v_cndmask_b32_e32 v5, v6, v5, vcc
	v_div_scale_f32 v6, s[2:3], v5, v5, 1.0
	v_rcp_f32_e32 v7, v6
	s_or_b32 s2, s54, s61
	v_or_b32_e32 v212, s2, v161
	v_fma_f32 v8, -v6, v7, 1.0
	v_fmac_f32_e32 v7, v8, v7
	v_div_scale_f32 v8, vcc, 1.0, v5, 1.0
	v_mul_f32_e32 v9, v8, v7
	v_fma_f32 v10, -v6, v9, v8
	v_fmac_f32_e32 v9, v10, v7
	v_fma_f32 v6, -v6, v9, v8
	v_div_fmas_f32 v6, v6, v7, v9
	v_div_fixup_f32 v6, v6, v5, 1.0
	v_pk_mul_f32 v[0:1], v[0:1], v[6:7] op_sel_hi:[1,0]
	s_waitcnt vmcnt(31)
	v_lshlrev_b32_e32 v8, 16, v156
	v_and_b32_e32 v9, 0xffff0000, v156
	v_pk_mul_f32 v[2:3], v[2:3], v[6:7] op_sel_hi:[1,0]
	v_lshlrev_b32_e32 v6, 16, v157
	v_and_b32_e32 v7, 0xffff0000, v157
	v_pk_mul_f32 v[0:1], v[0:1], v[8:9]
	v_pk_mul_f32 v[2:3], v[2:3], v[6:7]
	v_cvt_pk_bf16_f32 v0, v0, v1
	v_cvt_pk_bf16_f32 v1, v2, v3
	v_lshl_add_u64 v[2:3], v[212:213], 1, s[6:7]
	global_store_dwordx2 v[2:3], v[0:1], off
	v_add_u32_e32 v0, s62, v4
	ds_read_b128 v[0:3], v0
	s_waitcnt lgkmcnt(0)
	v_mov_b32_e32 v6, v1
	v_mov_b32_e32 v7, v2
	v_mov_b32_e32 v8, v0
	v_mov_b32_e32 v9, v3
	v_pk_add_f32 v[6:7], v[6:7], v[8:9]
	s_nop 0
	v_add_f32_e32 v5, v6, v7
	s_nop 1
	v_add_f32_dpp v5, v5, v5 quad_perm:[1,0,3,2] row_mask:0xf bank_mask:0xf
	s_nop 1
	v_add_f32_dpp v5, v5, v5 quad_perm:[2,3,0,1] row_mask:0xf bank_mask:0xf
	s_nop 1
	v_add_f32_dpp v5, v5, v5 row_half_mirror row_mask:0xf bank_mask:0xf
	s_nop 1
	v_add_f32_dpp v5, v5, v5 row_mirror row_mask:0xf bank_mask:0xf
	v_mov_b32_e32 v6, v5
	s_nop 1
	v_permlane16_swap_b32_e32 v5, v6
	v_add_f32_e32 v5, v5, v6
	v_mov_b32_e32 v6, v5
	s_nop 1
	v_permlane32_swap_b32_e32 v5, v6
	v_add_f32_e32 v5, v5, v6
	v_fmamk_f32 v1, v5, 0xbb800000, v1
	v_fmamk_f32 v0, v5, 0xbb800000, v0
	v_fmamk_f32 v3, v5, 0xbb800000, v3
	v_fmac_f32_e32 v2, 0xbb800000, v5
	v_pk_mul_f32 v[6:7], v[2:3], v[2:3]
	v_pk_mul_f32 v[8:9], v[0:1], v[0:1]
	s_nop 0
	v_pk_mov_b32 v[10:11], v[8:9], v[6:7] op_sel:[1,0]
	v_mov_b32_e32 v9, v7
	v_pk_add_f32 v[6:7], v[10:11], v[8:9]
	s_nop 0
	v_add_f32_e32 v5, v6, v7
	s_nop 1
	v_add_f32_dpp v5, v5, v5 quad_perm:[1,0,3,2] row_mask:0xf bank_mask:0xf
	s_nop 1
	v_add_f32_dpp v5, v5, v5 quad_perm:[2,3,0,1] row_mask:0xf bank_mask:0xf
	s_nop 1
	v_add_f32_dpp v5, v5, v5 row_half_mirror row_mask:0xf bank_mask:0xf
	s_nop 1
	v_add_f32_dpp v5, v5, v5 row_mirror row_mask:0xf bank_mask:0xf
	v_mov_b32_e32 v6, v5
	s_nop 1
	v_permlane16_swap_b32_e32 v5, v6
	v_add_f32_e32 v5, v5, v6
	v_mov_b32_e32 v6, v5
	s_nop 1
	v_permlane32_swap_b32_e32 v5, v6
	v_add_f32_e32 v5, v5, v6
	v_fmamk_f32 v5, v5, 0x3b800000, v251
	v_cmp_gt_f32_e32 vcc, s19, v5
	v_mul_f32_e32 v6, 0x4f800000, v5
	s_nop 0
	v_cndmask_b32_e32 v5, v5, v6, vcc
	v_sqrt_f32_e32 v6, v5
	s_nop 0
	v_add_u32_e32 v7, -1, v6
	v_fma_f32 v8, -v7, v6, v5
	v_cmp_ge_f32_e64 s[2:3], 0, v8
	v_add_u32_e32 v8, 1, v6
	s_nop 0
	v_cndmask_b32_e64 v7, v6, v7, s[2:3]
	v_fma_f32 v6, -v8, v6, v5
	v_cmp_lt_f32_e64 s[2:3], 0, v6
	s_nop 1
	v_cndmask_b32_e64 v6, v7, v8, s[2:3]
	v_mul_f32_e32 v7, 0x37800000, v6
	v_cndmask_b32_e32 v6, v6, v7, vcc
	v_cmp_class_f32_e32 vcc, v5, v252
	s_nop 1
	v_cndmask_b32_e32 v5, v6, v5, vcc
	v_div_scale_f32 v6, s[2:3], v5, v5, 1.0
	v_rcp_f32_e32 v7, v6
	s_or_b32 s2, s54, s63
	v_or_b32_e32 v212, s2, v161
	v_fma_f32 v8, -v6, v7, 1.0
	v_fmac_f32_e32 v7, v8, v7
	v_div_scale_f32 v8, vcc, 1.0, v5, 1.0
	v_mul_f32_e32 v9, v8, v7
	v_fma_f32 v10, -v6, v9, v8
	v_fmac_f32_e32 v9, v10, v7
	v_fma_f32 v6, -v6, v9, v8
	v_div_fmas_f32 v6, v6, v7, v9
	v_div_fixup_f32 v6, v6, v5, 1.0
	v_pk_mul_f32 v[0:1], v[0:1], v[6:7] op_sel_hi:[1,0]
	s_waitcnt vmcnt(31)
	v_lshlrev_b32_e32 v8, 16, v154
	v_and_b32_e32 v9, 0xffff0000, v154
	v_pk_mul_f32 v[2:3], v[2:3], v[6:7] op_sel_hi:[1,0]
	v_lshlrev_b32_e32 v6, 16, v155
	v_and_b32_e32 v7, 0xffff0000, v155
	v_pk_mul_f32 v[0:1], v[0:1], v[8:9]
	v_pk_mul_f32 v[2:3], v[2:3], v[6:7]
	v_cvt_pk_bf16_f32 v0, v0, v1
	v_cvt_pk_bf16_f32 v1, v2, v3
	v_lshl_add_u64 v[2:3], v[212:213], 1, s[6:7]
	global_store_dwordx2 v[2:3], v[0:1], off
	v_add_u32_e32 v0, s64, v4
	ds_read_b128 v[0:3], v0
	s_waitcnt lgkmcnt(0)
	v_mov_b32_e32 v6, v1
	v_mov_b32_e32 v7, v2
	v_mov_b32_e32 v8, v0
	v_mov_b32_e32 v9, v3
	v_pk_add_f32 v[6:7], v[6:7], v[8:9]
	s_nop 0
	v_add_f32_e32 v5, v6, v7
	s_nop 1
	v_add_f32_dpp v5, v5, v5 quad_perm:[1,0,3,2] row_mask:0xf bank_mask:0xf
	s_nop 1
	v_add_f32_dpp v5, v5, v5 quad_perm:[2,3,0,1] row_mask:0xf bank_mask:0xf
	s_nop 1
	v_add_f32_dpp v5, v5, v5 row_half_mirror row_mask:0xf bank_mask:0xf
	s_nop 1
	v_add_f32_dpp v5, v5, v5 row_mirror row_mask:0xf bank_mask:0xf
	v_mov_b32_e32 v6, v5
	s_nop 1
	v_permlane16_swap_b32_e32 v5, v6
	v_add_f32_e32 v5, v5, v6
	v_mov_b32_e32 v6, v5
	s_nop 1
	v_permlane32_swap_b32_e32 v5, v6
	v_add_f32_e32 v5, v5, v6
	v_fmamk_f32 v1, v5, 0xbb800000, v1
	v_fmamk_f32 v0, v5, 0xbb800000, v0
	v_fmamk_f32 v3, v5, 0xbb800000, v3
	v_fmac_f32_e32 v2, 0xbb800000, v5
	v_pk_mul_f32 v[6:7], v[2:3], v[2:3]
	v_pk_mul_f32 v[8:9], v[0:1], v[0:1]
	s_nop 0
	v_pk_mov_b32 v[10:11], v[8:9], v[6:7] op_sel:[1,0]
	v_mov_b32_e32 v9, v7
	v_pk_add_f32 v[6:7], v[10:11], v[8:9]
	s_nop 0
	v_add_f32_e32 v5, v6, v7
	s_nop 1
	v_add_f32_dpp v5, v5, v5 quad_perm:[1,0,3,2] row_mask:0xf bank_mask:0xf
	s_nop 1
	v_add_f32_dpp v5, v5, v5 quad_perm:[2,3,0,1] row_mask:0xf bank_mask:0xf
	s_nop 1
	v_add_f32_dpp v5, v5, v5 row_half_mirror row_mask:0xf bank_mask:0xf
	s_nop 1
	v_add_f32_dpp v5, v5, v5 row_mirror row_mask:0xf bank_mask:0xf
	v_mov_b32_e32 v6, v5
	s_nop 1
	v_permlane16_swap_b32_e32 v5, v6
	v_add_f32_e32 v5, v5, v6
	v_mov_b32_e32 v6, v5
	s_nop 1
	v_permlane32_swap_b32_e32 v5, v6
	v_add_f32_e32 v5, v5, v6
	v_fmamk_f32 v5, v5, 0x3b800000, v251
	v_cmp_gt_f32_e32 vcc, s19, v5
	v_mul_f32_e32 v6, 0x4f800000, v5
	s_nop 0
	v_cndmask_b32_e32 v5, v5, v6, vcc
	v_sqrt_f32_e32 v6, v5
	s_nop 0
	v_add_u32_e32 v7, -1, v6
	v_fma_f32 v8, -v7, v6, v5
	v_cmp_ge_f32_e64 s[2:3], 0, v8
	v_add_u32_e32 v8, 1, v6
	s_nop 0
	v_cndmask_b32_e64 v7, v6, v7, s[2:3]
	v_fma_f32 v6, -v8, v6, v5
	v_cmp_lt_f32_e64 s[2:3], 0, v6
	s_nop 1
	v_cndmask_b32_e64 v6, v7, v8, s[2:3]
	v_mul_f32_e32 v7, 0x37800000, v6
	v_cndmask_b32_e32 v6, v6, v7, vcc
	v_cmp_class_f32_e32 vcc, v5, v252
	s_nop 1
	v_cndmask_b32_e32 v5, v6, v5, vcc
	v_div_scale_f32 v6, s[2:3], v5, v5, 1.0
	v_rcp_f32_e32 v7, v6
	s_or_b32 s2, s54, s65
	v_or_b32_e32 v212, s2, v161
	v_fma_f32 v8, -v6, v7, 1.0
	v_fmac_f32_e32 v7, v8, v7
	v_div_scale_f32 v8, vcc, 1.0, v5, 1.0
	v_mul_f32_e32 v9, v8, v7
	v_fma_f32 v10, -v6, v9, v8
	v_fmac_f32_e32 v9, v10, v7
	v_fma_f32 v6, -v6, v9, v8
	v_div_fmas_f32 v6, v6, v7, v9
	v_div_fixup_f32 v6, v6, v5, 1.0
	v_pk_mul_f32 v[0:1], v[0:1], v[6:7] op_sel_hi:[1,0]
	s_waitcnt vmcnt(31)
	v_lshlrev_b32_e32 v8, 16, v152
	v_and_b32_e32 v9, 0xffff0000, v152
	v_pk_mul_f32 v[2:3], v[2:3], v[6:7] op_sel_hi:[1,0]
	v_lshlrev_b32_e32 v6, 16, v153
	v_and_b32_e32 v7, 0xffff0000, v153
	v_pk_mul_f32 v[0:1], v[0:1], v[8:9]
	v_pk_mul_f32 v[2:3], v[2:3], v[6:7]
	v_cvt_pk_bf16_f32 v0, v0, v1
	v_cvt_pk_bf16_f32 v1, v2, v3
	v_lshl_add_u64 v[2:3], v[212:213], 1, s[6:7]
	global_store_dwordx2 v[2:3], v[0:1], off
	v_add_u32_e32 v0, s78, v4
	ds_read_b128 v[0:3], v0
	s_waitcnt lgkmcnt(0)
	v_mov_b32_e32 v6, v1
	v_mov_b32_e32 v7, v2
	v_mov_b32_e32 v8, v0
	v_mov_b32_e32 v9, v3
	v_pk_add_f32 v[6:7], v[6:7], v[8:9]
	s_nop 0
	v_add_f32_e32 v5, v6, v7
	s_nop 1
	v_add_f32_dpp v5, v5, v5 quad_perm:[1,0,3,2] row_mask:0xf bank_mask:0xf
	s_nop 1
	v_add_f32_dpp v5, v5, v5 quad_perm:[2,3,0,1] row_mask:0xf bank_mask:0xf
	s_nop 1
	v_add_f32_dpp v5, v5, v5 row_half_mirror row_mask:0xf bank_mask:0xf
	s_nop 1
	v_add_f32_dpp v5, v5, v5 row_mirror row_mask:0xf bank_mask:0xf
	v_mov_b32_e32 v6, v5
	s_nop 1
	v_permlane16_swap_b32_e32 v5, v6
	v_add_f32_e32 v5, v5, v6
	v_mov_b32_e32 v6, v5
	s_nop 1
	v_permlane32_swap_b32_e32 v5, v6
	v_add_f32_e32 v5, v5, v6
	v_fmamk_f32 v1, v5, 0xbb800000, v1
	v_fmamk_f32 v0, v5, 0xbb800000, v0
	v_fmamk_f32 v3, v5, 0xbb800000, v3
	v_fmac_f32_e32 v2, 0xbb800000, v5
	v_pk_mul_f32 v[6:7], v[2:3], v[2:3]
	v_pk_mul_f32 v[8:9], v[0:1], v[0:1]
	s_nop 0
	v_pk_mov_b32 v[10:11], v[8:9], v[6:7] op_sel:[1,0]
	v_mov_b32_e32 v9, v7
	v_pk_add_f32 v[6:7], v[10:11], v[8:9]
	s_nop 0
	v_add_f32_e32 v5, v6, v7
	s_nop 1
	v_add_f32_dpp v5, v5, v5 quad_perm:[1,0,3,2] row_mask:0xf bank_mask:0xf
	s_nop 1
	v_add_f32_dpp v5, v5, v5 quad_perm:[2,3,0,1] row_mask:0xf bank_mask:0xf
	s_nop 1
	v_add_f32_dpp v5, v5, v5 row_half_mirror row_mask:0xf bank_mask:0xf
	s_nop 1
	v_add_f32_dpp v5, v5, v5 row_mirror row_mask:0xf bank_mask:0xf
	v_mov_b32_e32 v6, v5
	s_nop 1
	v_permlane16_swap_b32_e32 v5, v6
	v_add_f32_e32 v5, v5, v6
	v_mov_b32_e32 v6, v5
	s_nop 1
	v_permlane32_swap_b32_e32 v5, v6
	v_add_f32_e32 v5, v5, v6
	v_fmamk_f32 v5, v5, 0x3b800000, v251
	v_cmp_gt_f32_e32 vcc, s19, v5
	v_mul_f32_e32 v6, 0x4f800000, v5
	s_nop 0
	v_cndmask_b32_e32 v5, v5, v6, vcc
	v_sqrt_f32_e32 v6, v5
	s_nop 0
	v_add_u32_e32 v7, -1, v6
	v_fma_f32 v8, -v7, v6, v5
	v_cmp_ge_f32_e64 s[2:3], 0, v8
	v_add_u32_e32 v8, 1, v6
	s_nop 0
	v_cndmask_b32_e64 v7, v6, v7, s[2:3]
	v_fma_f32 v6, -v8, v6, v5
	v_cmp_lt_f32_e64 s[2:3], 0, v6
	s_nop 1
	v_cndmask_b32_e64 v6, v7, v8, s[2:3]
	v_mul_f32_e32 v7, 0x37800000, v6
	v_cndmask_b32_e32 v6, v6, v7, vcc
	v_cmp_class_f32_e32 vcc, v5, v252
	s_nop 1
	v_cndmask_b32_e32 v5, v6, v5, vcc
	v_div_scale_f32 v6, s[2:3], v5, v5, 1.0
	v_rcp_f32_e32 v7, v6
	s_or_b32 s2, s54, s79
	v_or_b32_e32 v212, s2, v161
	v_fma_f32 v8, -v6, v7, 1.0
	v_fmac_f32_e32 v7, v8, v7
	v_div_scale_f32 v8, vcc, 1.0, v5, 1.0
	v_mul_f32_e32 v9, v8, v7
	v_fma_f32 v10, -v6, v9, v8
	v_fmac_f32_e32 v9, v10, v7
	v_fma_f32 v6, -v6, v9, v8
	v_div_fmas_f32 v6, v6, v7, v9
	v_div_fixup_f32 v6, v6, v5, 1.0
	v_pk_mul_f32 v[0:1], v[0:1], v[6:7] op_sel_hi:[1,0]
	s_waitcnt vmcnt(31)
	v_lshlrev_b32_e32 v8, 16, v150
	v_and_b32_e32 v9, 0xffff0000, v150
	v_pk_mul_f32 v[2:3], v[2:3], v[6:7] op_sel_hi:[1,0]
	v_lshlrev_b32_e32 v6, 16, v151
	v_and_b32_e32 v7, 0xffff0000, v151
	v_pk_mul_f32 v[0:1], v[0:1], v[8:9]
	v_pk_mul_f32 v[2:3], v[2:3], v[6:7]
	v_cvt_pk_bf16_f32 v0, v0, v1
	v_cvt_pk_bf16_f32 v1, v2, v3
	v_lshl_add_u64 v[2:3], v[212:213], 1, s[6:7]
	global_store_dwordx2 v[2:3], v[0:1], off
	v_add_u32_e32 v0, s88, v4
	ds_read_b128 v[0:3], v0
	s_waitcnt lgkmcnt(0)
	v_mov_b32_e32 v6, v1
	v_mov_b32_e32 v7, v2
	v_mov_b32_e32 v8, v0
	v_mov_b32_e32 v9, v3
	v_pk_add_f32 v[6:7], v[6:7], v[8:9]
	s_nop 0
	v_add_f32_e32 v5, v6, v7
	s_nop 1
	v_add_f32_dpp v5, v5, v5 quad_perm:[1,0,3,2] row_mask:0xf bank_mask:0xf
	s_nop 1
	v_add_f32_dpp v5, v5, v5 quad_perm:[2,3,0,1] row_mask:0xf bank_mask:0xf
	s_nop 1
	v_add_f32_dpp v5, v5, v5 row_half_mirror row_mask:0xf bank_mask:0xf
	s_nop 1
	v_add_f32_dpp v5, v5, v5 row_mirror row_mask:0xf bank_mask:0xf
	v_mov_b32_e32 v6, v5
	s_nop 1
	v_permlane16_swap_b32_e32 v5, v6
	v_add_f32_e32 v5, v5, v6
	v_mov_b32_e32 v6, v5
	s_nop 1
	v_permlane32_swap_b32_e32 v5, v6
	v_add_f32_e32 v5, v5, v6
	v_fmamk_f32 v1, v5, 0xbb800000, v1
	v_fmamk_f32 v0, v5, 0xbb800000, v0
	v_fmamk_f32 v3, v5, 0xbb800000, v3
	v_fmac_f32_e32 v2, 0xbb800000, v5
	v_pk_mul_f32 v[6:7], v[2:3], v[2:3]
	v_pk_mul_f32 v[8:9], v[0:1], v[0:1]
	s_nop 0
	v_pk_mov_b32 v[10:11], v[8:9], v[6:7] op_sel:[1,0]
	v_mov_b32_e32 v9, v7
	v_pk_add_f32 v[6:7], v[10:11], v[8:9]
	s_nop 0
	v_add_f32_e32 v5, v6, v7
	s_nop 1
	v_add_f32_dpp v5, v5, v5 quad_perm:[1,0,3,2] row_mask:0xf bank_mask:0xf
	s_nop 1
	v_add_f32_dpp v5, v5, v5 quad_perm:[2,3,0,1] row_mask:0xf bank_mask:0xf
	s_nop 1
	v_add_f32_dpp v5, v5, v5 row_half_mirror row_mask:0xf bank_mask:0xf
	s_nop 1
	v_add_f32_dpp v5, v5, v5 row_mirror row_mask:0xf bank_mask:0xf
	v_mov_b32_e32 v6, v5
	s_nop 1
	v_permlane16_swap_b32_e32 v5, v6
	v_add_f32_e32 v5, v5, v6
	v_mov_b32_e32 v6, v5
	s_nop 1
	v_permlane32_swap_b32_e32 v5, v6
	v_add_f32_e32 v5, v5, v6
	v_fmamk_f32 v5, v5, 0x3b800000, v251
	v_cmp_gt_f32_e32 vcc, s19, v5
	v_mul_f32_e32 v6, 0x4f800000, v5
	s_nop 0
	v_cndmask_b32_e32 v5, v5, v6, vcc
	v_sqrt_f32_e32 v6, v5
	s_nop 0
	v_add_u32_e32 v7, -1, v6
	v_fma_f32 v8, -v7, v6, v5
	v_cmp_ge_f32_e64 s[2:3], 0, v8
	v_add_u32_e32 v8, 1, v6
	s_nop 0
	v_cndmask_b32_e64 v7, v6, v7, s[2:3]
	v_fma_f32 v6, -v8, v6, v5
	v_cmp_lt_f32_e64 s[2:3], 0, v6
	s_nop 1
	v_cndmask_b32_e64 v6, v7, v8, s[2:3]
	v_mul_f32_e32 v7, 0x37800000, v6
	v_cndmask_b32_e32 v6, v6, v7, vcc
	v_cmp_class_f32_e32 vcc, v5, v252
	s_nop 1
	v_cndmask_b32_e32 v5, v6, v5, vcc
	v_div_scale_f32 v6, s[2:3], v5, v5, 1.0
	v_rcp_f32_e32 v7, v6
	s_or_b32 s2, s54, s89
	v_or_b32_e32 v212, s2, v161
	v_fma_f32 v8, -v6, v7, 1.0
	v_fmac_f32_e32 v7, v8, v7
	v_div_scale_f32 v8, vcc, 1.0, v5, 1.0
	v_mul_f32_e32 v9, v8, v7
	v_fma_f32 v10, -v6, v9, v8
	v_fmac_f32_e32 v9, v10, v7
	v_fma_f32 v6, -v6, v9, v8
	v_div_fmas_f32 v6, v6, v7, v9
	v_div_fixup_f32 v6, v6, v5, 1.0
	v_pk_mul_f32 v[0:1], v[0:1], v[6:7] op_sel_hi:[1,0]
	s_waitcnt vmcnt(31)
	v_lshlrev_b32_e32 v8, 16, v148
	v_and_b32_e32 v9, 0xffff0000, v148
	v_pk_mul_f32 v[2:3], v[2:3], v[6:7] op_sel_hi:[1,0]
	v_lshlrev_b32_e32 v6, 16, v149
	v_and_b32_e32 v7, 0xffff0000, v149
	v_pk_mul_f32 v[0:1], v[0:1], v[8:9]
	v_pk_mul_f32 v[2:3], v[2:3], v[6:7]
	v_cvt_pk_bf16_f32 v0, v0, v1
	v_cvt_pk_bf16_f32 v1, v2, v3
	v_lshl_add_u64 v[2:3], v[212:213], 1, s[6:7]
	global_store_dwordx2 v[2:3], v[0:1], off
	v_add_u32_e32 v0, s94, v4
	ds_read_b128 v[0:3], v0
	s_waitcnt lgkmcnt(0)
	v_mov_b32_e32 v6, v1
	v_mov_b32_e32 v7, v2
	v_mov_b32_e32 v8, v0
	v_mov_b32_e32 v9, v3
	v_pk_add_f32 v[6:7], v[6:7], v[8:9]
	s_nop 0
	v_add_f32_e32 v5, v6, v7
	s_nop 1
	v_add_f32_dpp v5, v5, v5 quad_perm:[1,0,3,2] row_mask:0xf bank_mask:0xf
	s_nop 1
	v_add_f32_dpp v5, v5, v5 quad_perm:[2,3,0,1] row_mask:0xf bank_mask:0xf
	s_nop 1
	v_add_f32_dpp v5, v5, v5 row_half_mirror row_mask:0xf bank_mask:0xf
	s_nop 1
	v_add_f32_dpp v5, v5, v5 row_mirror row_mask:0xf bank_mask:0xf
	v_mov_b32_e32 v6, v5
	s_nop 1
	v_permlane16_swap_b32_e32 v5, v6
	v_add_f32_e32 v5, v5, v6
	v_mov_b32_e32 v6, v5
	s_nop 1
	v_permlane32_swap_b32_e32 v5, v6
	v_add_f32_e32 v5, v5, v6
	v_fmamk_f32 v1, v5, 0xbb800000, v1
	v_fmamk_f32 v0, v5, 0xbb800000, v0
	v_fmamk_f32 v3, v5, 0xbb800000, v3
	v_fmac_f32_e32 v2, 0xbb800000, v5
	v_pk_mul_f32 v[6:7], v[2:3], v[2:3]
	v_pk_mul_f32 v[8:9], v[0:1], v[0:1]
	s_nop 0
	v_pk_mov_b32 v[10:11], v[8:9], v[6:7] op_sel:[1,0]
	v_mov_b32_e32 v9, v7
	v_pk_add_f32 v[6:7], v[10:11], v[8:9]
	s_nop 0
	v_add_f32_e32 v5, v6, v7
	s_nop 1
	v_add_f32_dpp v5, v5, v5 quad_perm:[1,0,3,2] row_mask:0xf bank_mask:0xf
	s_nop 1
	v_add_f32_dpp v5, v5, v5 quad_perm:[2,3,0,1] row_mask:0xf bank_mask:0xf
	s_nop 1
	v_add_f32_dpp v5, v5, v5 row_half_mirror row_mask:0xf bank_mask:0xf
	s_nop 1
	v_add_f32_dpp v5, v5, v5 row_mirror row_mask:0xf bank_mask:0xf
	v_mov_b32_e32 v6, v5
	s_nop 1
	v_permlane16_swap_b32_e32 v5, v6
	v_add_f32_e32 v5, v5, v6
	v_mov_b32_e32 v6, v5
	s_nop 1
	v_permlane32_swap_b32_e32 v5, v6
	v_add_f32_e32 v5, v5, v6
	v_fmamk_f32 v5, v5, 0x3b800000, v251
	v_cmp_gt_f32_e32 vcc, s19, v5
	v_mul_f32_e32 v6, 0x4f800000, v5
	s_nop 0
	v_cndmask_b32_e32 v5, v5, v6, vcc
	v_sqrt_f32_e32 v6, v5
	s_nop 0
	v_add_u32_e32 v7, -1, v6
	v_fma_f32 v8, -v7, v6, v5
	v_cmp_ge_f32_e64 s[2:3], 0, v8
	v_add_u32_e32 v8, 1, v6
	s_nop 0
	v_cndmask_b32_e64 v7, v6, v7, s[2:3]
	v_fma_f32 v6, -v8, v6, v5
	v_cmp_lt_f32_e64 s[2:3], 0, v6
	s_nop 1
	v_cndmask_b32_e64 v6, v7, v8, s[2:3]
	v_mul_f32_e32 v7, 0x37800000, v6
	v_cndmask_b32_e32 v6, v6, v7, vcc
	v_cmp_class_f32_e32 vcc, v5, v252
	s_nop 1
	v_cndmask_b32_e32 v5, v6, v5, vcc
	v_div_scale_f32 v6, s[2:3], v5, v5, 1.0
	v_rcp_f32_e32 v7, v6
	s_or_b32 s2, s54, s95
	v_or_b32_e32 v212, s2, v161
	v_fma_f32 v8, -v6, v7, 1.0
	v_fmac_f32_e32 v7, v8, v7
	v_div_scale_f32 v8, vcc, 1.0, v5, 1.0
	v_mul_f32_e32 v9, v8, v7
	v_fma_f32 v10, -v6, v9, v8
	v_fmac_f32_e32 v9, v10, v7
	v_fma_f32 v6, -v6, v9, v8
	v_div_fmas_f32 v6, v6, v7, v9
	v_div_fixup_f32 v6, v6, v5, 1.0
	v_pk_mul_f32 v[0:1], v[0:1], v[6:7] op_sel_hi:[1,0]
	s_waitcnt vmcnt(31)
	v_lshlrev_b32_e32 v8, 16, v146
	v_and_b32_e32 v9, 0xffff0000, v146
	v_pk_mul_f32 v[2:3], v[2:3], v[6:7] op_sel_hi:[1,0]
	v_lshlrev_b32_e32 v6, 16, v147
	v_and_b32_e32 v7, 0xffff0000, v147
	v_pk_mul_f32 v[0:1], v[0:1], v[8:9]
	v_pk_mul_f32 v[2:3], v[2:3], v[6:7]
	v_cvt_pk_bf16_f32 v0, v0, v1
	v_cvt_pk_bf16_f32 v1, v2, v3
	v_lshl_add_u64 v[2:3], v[212:213], 1, s[6:7]
	global_store_dwordx2 v[2:3], v[0:1], off
	v_add_u32_e32 v0, s96, v4
	ds_read_b128 v[0:3], v0
	s_waitcnt lgkmcnt(0)
	v_mov_b32_e32 v6, v1
	v_mov_b32_e32 v7, v2
	v_mov_b32_e32 v8, v0
	v_mov_b32_e32 v9, v3
	v_pk_add_f32 v[6:7], v[6:7], v[8:9]
	s_nop 0
	v_add_f32_e32 v5, v6, v7
	s_nop 1
	v_add_f32_dpp v5, v5, v5 quad_perm:[1,0,3,2] row_mask:0xf bank_mask:0xf
	s_nop 1
	v_add_f32_dpp v5, v5, v5 quad_perm:[2,3,0,1] row_mask:0xf bank_mask:0xf
	s_nop 1
	v_add_f32_dpp v5, v5, v5 row_half_mirror row_mask:0xf bank_mask:0xf
	s_nop 1
	v_add_f32_dpp v5, v5, v5 row_mirror row_mask:0xf bank_mask:0xf
	v_mov_b32_e32 v6, v5
	s_nop 1
	v_permlane16_swap_b32_e32 v5, v6
	v_add_f32_e32 v5, v5, v6
	v_mov_b32_e32 v6, v5
	s_nop 1
	v_permlane32_swap_b32_e32 v5, v6
	v_add_f32_e32 v5, v5, v6
	v_fmamk_f32 v1, v5, 0xbb800000, v1
	v_fmamk_f32 v0, v5, 0xbb800000, v0
	v_fmamk_f32 v3, v5, 0xbb800000, v3
	v_fmac_f32_e32 v2, 0xbb800000, v5
	v_pk_mul_f32 v[6:7], v[2:3], v[2:3]
	v_pk_mul_f32 v[8:9], v[0:1], v[0:1]
	s_nop 0
	v_pk_mov_b32 v[10:11], v[8:9], v[6:7] op_sel:[1,0]
	v_mov_b32_e32 v9, v7
	v_pk_add_f32 v[6:7], v[10:11], v[8:9]
	s_nop 0
	v_add_f32_e32 v5, v6, v7
	s_nop 1
	v_add_f32_dpp v5, v5, v5 quad_perm:[1,0,3,2] row_mask:0xf bank_mask:0xf
	s_nop 1
	v_add_f32_dpp v5, v5, v5 quad_perm:[2,3,0,1] row_mask:0xf bank_mask:0xf
	s_nop 1
	v_add_f32_dpp v5, v5, v5 row_half_mirror row_mask:0xf bank_mask:0xf
	s_nop 1
	v_add_f32_dpp v5, v5, v5 row_mirror row_mask:0xf bank_mask:0xf
	v_mov_b32_e32 v6, v5
	s_nop 1
	v_permlane16_swap_b32_e32 v5, v6
	v_add_f32_e32 v5, v5, v6
	v_mov_b32_e32 v6, v5
	s_nop 1
	v_permlane32_swap_b32_e32 v5, v6
	v_add_f32_e32 v5, v5, v6
	v_fmamk_f32 v5, v5, 0x3b800000, v251
	v_cmp_gt_f32_e32 vcc, s19, v5
	v_mul_f32_e32 v6, 0x4f800000, v5
	s_nop 0
	v_cndmask_b32_e32 v5, v5, v6, vcc
	v_sqrt_f32_e32 v6, v5
	s_nop 0
	v_add_u32_e32 v7, -1, v6
	v_fma_f32 v8, -v7, v6, v5
	v_cmp_ge_f32_e64 s[2:3], 0, v8
	v_add_u32_e32 v8, 1, v6
	s_nop 0
	v_cndmask_b32_e64 v7, v6, v7, s[2:3]
	v_fma_f32 v6, -v8, v6, v5
	v_cmp_lt_f32_e64 s[2:3], 0, v6
	s_nop 1
	v_cndmask_b32_e64 v6, v7, v8, s[2:3]
	v_mul_f32_e32 v7, 0x37800000, v6
	v_cndmask_b32_e32 v6, v6, v7, vcc
	v_cmp_class_f32_e32 vcc, v5, v252
	s_nop 1
	v_cndmask_b32_e32 v5, v6, v5, vcc
	v_div_scale_f32 v6, s[2:3], v5, v5, 1.0
	v_rcp_f32_e32 v7, v6
	s_or_b32 s2, s54, s97
	v_or_b32_e32 v212, s2, v161
	v_fma_f32 v8, -v6, v7, 1.0
	v_fmac_f32_e32 v7, v8, v7
	v_div_scale_f32 v8, vcc, 1.0, v5, 1.0
	v_mul_f32_e32 v9, v8, v7
	v_fma_f32 v10, -v6, v9, v8
	v_fmac_f32_e32 v9, v10, v7
	v_fma_f32 v6, -v6, v9, v8
	v_div_fmas_f32 v6, v6, v7, v9
	v_div_fixup_f32 v6, v6, v5, 1.0
	v_pk_mul_f32 v[0:1], v[0:1], v[6:7] op_sel_hi:[1,0]
	s_waitcnt vmcnt(31)
	v_lshlrev_b32_e32 v8, 16, v144
	v_and_b32_e32 v9, 0xffff0000, v144
	v_pk_mul_f32 v[2:3], v[2:3], v[6:7] op_sel_hi:[1,0]
	v_lshlrev_b32_e32 v6, 16, v145
	v_and_b32_e32 v7, 0xffff0000, v145
	v_pk_mul_f32 v[0:1], v[0:1], v[8:9]
	v_pk_mul_f32 v[2:3], v[2:3], v[6:7]
	v_cvt_pk_bf16_f32 v0, v0, v1
	v_cvt_pk_bf16_f32 v1, v2, v3
	v_lshl_add_u64 v[2:3], v[212:213], 1, s[6:7]
	global_store_dwordx2 v[2:3], v[0:1], off
	v_add_u32_e32 v0, s22, v4
	ds_read_b128 v[0:3], v0
	s_waitcnt lgkmcnt(0)
	v_mov_b32_e32 v6, v1
	v_mov_b32_e32 v7, v2
	v_mov_b32_e32 v8, v0
	v_mov_b32_e32 v9, v3
	v_pk_add_f32 v[6:7], v[6:7], v[8:9]
	s_nop 0
	v_add_f32_e32 v5, v6, v7
	s_nop 1
	v_add_f32_dpp v5, v5, v5 quad_perm:[1,0,3,2] row_mask:0xf bank_mask:0xf
	s_nop 1
	v_add_f32_dpp v5, v5, v5 quad_perm:[2,3,0,1] row_mask:0xf bank_mask:0xf
	s_nop 1
	v_add_f32_dpp v5, v5, v5 row_half_mirror row_mask:0xf bank_mask:0xf
	s_nop 1
	v_add_f32_dpp v5, v5, v5 row_mirror row_mask:0xf bank_mask:0xf
	v_mov_b32_e32 v6, v5
	s_nop 1
	v_permlane16_swap_b32_e32 v5, v6
	v_add_f32_e32 v5, v5, v6
	v_mov_b32_e32 v6, v5
	s_nop 1
	v_permlane32_swap_b32_e32 v5, v6
	v_add_f32_e32 v5, v5, v6
	v_fmamk_f32 v1, v5, 0xbb800000, v1
	v_fmamk_f32 v0, v5, 0xbb800000, v0
	v_fmamk_f32 v3, v5, 0xbb800000, v3
	v_fmac_f32_e32 v2, 0xbb800000, v5
	v_pk_mul_f32 v[6:7], v[2:3], v[2:3]
	v_pk_mul_f32 v[8:9], v[0:1], v[0:1]
	s_nop 0
	v_pk_mov_b32 v[10:11], v[8:9], v[6:7] op_sel:[1,0]
	v_mov_b32_e32 v9, v7
	v_pk_add_f32 v[6:7], v[10:11], v[8:9]
	s_nop 0
	v_add_f32_e32 v5, v6, v7
	s_nop 1
	v_add_f32_dpp v5, v5, v5 quad_perm:[1,0,3,2] row_mask:0xf bank_mask:0xf
	s_nop 1
	v_add_f32_dpp v5, v5, v5 quad_perm:[2,3,0,1] row_mask:0xf bank_mask:0xf
	s_nop 1
	v_add_f32_dpp v5, v5, v5 row_half_mirror row_mask:0xf bank_mask:0xf
	s_nop 1
	v_add_f32_dpp v5, v5, v5 row_mirror row_mask:0xf bank_mask:0xf
	v_mov_b32_e32 v6, v5
	s_nop 1
	v_permlane16_swap_b32_e32 v5, v6
	v_add_f32_e32 v5, v5, v6
	v_mov_b32_e32 v6, v5
	s_nop 1
	v_permlane32_swap_b32_e32 v5, v6
	v_add_f32_e32 v5, v5, v6
	v_fmamk_f32 v5, v5, 0x3b800000, v251
	v_cmp_gt_f32_e32 vcc, s19, v5
	v_mul_f32_e32 v6, 0x4f800000, v5
	s_nop 0
	v_cndmask_b32_e32 v5, v5, v6, vcc
	v_sqrt_f32_e32 v6, v5
	s_nop 0
	v_add_u32_e32 v7, -1, v6
	v_fma_f32 v8, -v7, v6, v5
	v_cmp_ge_f32_e64 s[2:3], 0, v8
	v_add_u32_e32 v8, 1, v6
	s_nop 0
	v_cndmask_b32_e64 v7, v6, v7, s[2:3]
	v_fma_f32 v6, -v8, v6, v5
	v_cmp_lt_f32_e64 s[2:3], 0, v6
	s_nop 1
	v_cndmask_b32_e64 v6, v7, v8, s[2:3]
	v_mul_f32_e32 v7, 0x37800000, v6
	v_cndmask_b32_e32 v6, v6, v7, vcc
	v_cmp_class_f32_e32 vcc, v5, v252
	s_nop 1
	v_cndmask_b32_e32 v5, v6, v5, vcc
	v_div_scale_f32 v6, s[2:3], v5, v5, 1.0
	v_rcp_f32_e32 v7, v6
	s_or_b32 s2, s54, s23
	v_or_b32_e32 v212, s2, v161
	v_fma_f32 v8, -v6, v7, 1.0
	v_fmac_f32_e32 v7, v8, v7
	v_div_scale_f32 v8, vcc, 1.0, v5, 1.0
	v_mul_f32_e32 v9, v8, v7
	v_fma_f32 v10, -v6, v9, v8
	v_fmac_f32_e32 v9, v10, v7
	v_fma_f32 v6, -v6, v9, v8
	v_div_fmas_f32 v6, v6, v7, v9
	v_div_fixup_f32 v6, v6, v5, 1.0
	v_pk_mul_f32 v[0:1], v[0:1], v[6:7] op_sel_hi:[1,0]
	s_waitcnt vmcnt(31)
	v_lshlrev_b32_e32 v8, 16, v78
	v_and_b32_e32 v9, 0xffff0000, v78
	v_pk_mul_f32 v[2:3], v[2:3], v[6:7] op_sel_hi:[1,0]
	v_lshlrev_b32_e32 v6, 16, v79
	v_and_b32_e32 v7, 0xffff0000, v79
	v_pk_mul_f32 v[0:1], v[0:1], v[8:9]
	v_pk_mul_f32 v[2:3], v[2:3], v[6:7]
	v_cvt_pk_bf16_f32 v0, v0, v1
	v_cvt_pk_bf16_f32 v1, v2, v3
	v_lshl_add_u64 v[2:3], v[212:213], 1, s[6:7]
	global_store_dwordx2 v[2:3], v[0:1], off
	v_add_u32_e32 v0, s26, v4
	ds_read_b128 v[0:3], v0
	s_waitcnt lgkmcnt(0)
	v_mov_b32_e32 v6, v1
	v_mov_b32_e32 v7, v2
	v_mov_b32_e32 v8, v0
	v_mov_b32_e32 v9, v3
	v_pk_add_f32 v[6:7], v[6:7], v[8:9]
	s_nop 0
	v_add_f32_e32 v5, v6, v7
	s_nop 1
	v_add_f32_dpp v5, v5, v5 quad_perm:[1,0,3,2] row_mask:0xf bank_mask:0xf
	s_nop 1
	v_add_f32_dpp v5, v5, v5 quad_perm:[2,3,0,1] row_mask:0xf bank_mask:0xf
	s_nop 1
	v_add_f32_dpp v5, v5, v5 row_half_mirror row_mask:0xf bank_mask:0xf
	s_nop 1
	v_add_f32_dpp v5, v5, v5 row_mirror row_mask:0xf bank_mask:0xf
	v_mov_b32_e32 v6, v5
	s_nop 1
	v_permlane16_swap_b32_e32 v5, v6
	v_add_f32_e32 v5, v5, v6
	v_mov_b32_e32 v6, v5
	s_nop 1
	v_permlane32_swap_b32_e32 v5, v6
	v_add_f32_e32 v5, v5, v6
	v_fmamk_f32 v1, v5, 0xbb800000, v1
	v_fmamk_f32 v0, v5, 0xbb800000, v0
	v_fmamk_f32 v3, v5, 0xbb800000, v3
	v_fmac_f32_e32 v2, 0xbb800000, v5
	v_pk_mul_f32 v[6:7], v[2:3], v[2:3]
	v_pk_mul_f32 v[8:9], v[0:1], v[0:1]
	s_nop 0
	v_pk_mov_b32 v[10:11], v[8:9], v[6:7] op_sel:[1,0]
	v_mov_b32_e32 v9, v7
	v_pk_add_f32 v[6:7], v[10:11], v[8:9]
	s_nop 0
	v_add_f32_e32 v5, v6, v7
	s_nop 1
	v_add_f32_dpp v5, v5, v5 quad_perm:[1,0,3,2] row_mask:0xf bank_mask:0xf
	s_nop 1
	v_add_f32_dpp v5, v5, v5 quad_perm:[2,3,0,1] row_mask:0xf bank_mask:0xf
	s_nop 1
	v_add_f32_dpp v5, v5, v5 row_half_mirror row_mask:0xf bank_mask:0xf
	s_nop 1
	v_add_f32_dpp v5, v5, v5 row_mirror row_mask:0xf bank_mask:0xf
	v_mov_b32_e32 v6, v5
	s_nop 1
	v_permlane16_swap_b32_e32 v5, v6
	v_add_f32_e32 v5, v5, v6
	v_mov_b32_e32 v6, v5
	s_nop 1
	v_permlane32_swap_b32_e32 v5, v6
	v_add_f32_e32 v5, v5, v6
	v_fmamk_f32 v5, v5, 0x3b800000, v251
	v_cmp_gt_f32_e32 vcc, s19, v5
	v_mul_f32_e32 v6, 0x4f800000, v5
	s_nop 0
	v_cndmask_b32_e32 v5, v5, v6, vcc
	v_sqrt_f32_e32 v6, v5
	s_nop 0
	v_add_u32_e32 v7, -1, v6
	v_fma_f32 v8, -v7, v6, v5
	v_cmp_ge_f32_e64 s[2:3], 0, v8
	v_add_u32_e32 v8, 1, v6
	s_nop 0
	v_cndmask_b32_e64 v7, v6, v7, s[2:3]
	v_fma_f32 v6, -v8, v6, v5
	v_cmp_lt_f32_e64 s[2:3], 0, v6
	s_nop 1
	v_cndmask_b32_e64 v6, v7, v8, s[2:3]
	v_mul_f32_e32 v7, 0x37800000, v6
	v_cndmask_b32_e32 v6, v6, v7, vcc
	v_cmp_class_f32_e32 vcc, v5, v252
	s_nop 1
	v_cndmask_b32_e32 v5, v6, v5, vcc
	v_div_scale_f32 v6, s[2:3], v5, v5, 1.0
	v_rcp_f32_e32 v7, v6
	s_or_b32 s2, s54, s27
	v_or_b32_e32 v212, s2, v161
	v_fma_f32 v8, -v6, v7, 1.0
	v_fmac_f32_e32 v7, v8, v7
	v_div_scale_f32 v8, vcc, 1.0, v5, 1.0
	v_mul_f32_e32 v9, v8, v7
	v_fma_f32 v10, -v6, v9, v8
	v_fmac_f32_e32 v9, v10, v7
	v_fma_f32 v6, -v6, v9, v8
	v_div_fmas_f32 v6, v6, v7, v9
	v_div_fixup_f32 v6, v6, v5, 1.0
	v_pk_mul_f32 v[0:1], v[0:1], v[6:7] op_sel_hi:[1,0]
	s_waitcnt vmcnt(31)
	v_lshlrev_b32_e32 v8, 16, v76
	v_and_b32_e32 v9, 0xffff0000, v76
	v_pk_mul_f32 v[2:3], v[2:3], v[6:7] op_sel_hi:[1,0]
	v_lshlrev_b32_e32 v6, 16, v77
	v_and_b32_e32 v7, 0xffff0000, v77
	v_pk_mul_f32 v[0:1], v[0:1], v[8:9]
	v_pk_mul_f32 v[2:3], v[2:3], v[6:7]
	v_cvt_pk_bf16_f32 v0, v0, v1
	v_cvt_pk_bf16_f32 v1, v2, v3
	v_lshl_add_u64 v[2:3], v[212:213], 1, s[6:7]
	global_store_dwordx2 v[2:3], v[0:1], off
	v_add_u32_e32 v0, s30, v4
	ds_read_b128 v[0:3], v0
	s_waitcnt lgkmcnt(0)
	v_mov_b32_e32 v6, v1
	v_mov_b32_e32 v7, v2
	v_mov_b32_e32 v8, v0
	v_mov_b32_e32 v9, v3
	v_pk_add_f32 v[6:7], v[6:7], v[8:9]
	s_nop 0
	v_add_f32_e32 v5, v6, v7
	s_nop 1
	v_add_f32_dpp v5, v5, v5 quad_perm:[1,0,3,2] row_mask:0xf bank_mask:0xf
	s_nop 1
	v_add_f32_dpp v5, v5, v5 quad_perm:[2,3,0,1] row_mask:0xf bank_mask:0xf
	s_nop 1
	v_add_f32_dpp v5, v5, v5 row_half_mirror row_mask:0xf bank_mask:0xf
	s_nop 1
	v_add_f32_dpp v5, v5, v5 row_mirror row_mask:0xf bank_mask:0xf
	v_mov_b32_e32 v6, v5
	s_nop 1
	v_permlane16_swap_b32_e32 v5, v6
	v_add_f32_e32 v5, v5, v6
	v_mov_b32_e32 v6, v5
	s_nop 1
	v_permlane32_swap_b32_e32 v5, v6
	v_add_f32_e32 v5, v5, v6
	v_fmamk_f32 v1, v5, 0xbb800000, v1
	v_fmamk_f32 v0, v5, 0xbb800000, v0
	v_fmamk_f32 v3, v5, 0xbb800000, v3
	v_fmac_f32_e32 v2, 0xbb800000, v5
	v_pk_mul_f32 v[6:7], v[2:3], v[2:3]
	v_pk_mul_f32 v[8:9], v[0:1], v[0:1]
	s_nop 0
	v_pk_mov_b32 v[10:11], v[8:9], v[6:7] op_sel:[1,0]
	v_mov_b32_e32 v9, v7
	v_pk_add_f32 v[6:7], v[10:11], v[8:9]
	s_nop 0
	v_add_f32_e32 v5, v6, v7
	s_nop 1
	v_add_f32_dpp v5, v5, v5 quad_perm:[1,0,3,2] row_mask:0xf bank_mask:0xf
	s_nop 1
	v_add_f32_dpp v5, v5, v5 quad_perm:[2,3,0,1] row_mask:0xf bank_mask:0xf
	s_nop 1
	v_add_f32_dpp v5, v5, v5 row_half_mirror row_mask:0xf bank_mask:0xf
	s_nop 1
	v_add_f32_dpp v5, v5, v5 row_mirror row_mask:0xf bank_mask:0xf
	v_mov_b32_e32 v6, v5
	s_nop 1
	v_permlane16_swap_b32_e32 v5, v6
	v_add_f32_e32 v5, v5, v6
	v_mov_b32_e32 v6, v5
	s_nop 1
	v_permlane32_swap_b32_e32 v5, v6
	v_add_f32_e32 v5, v5, v6
	v_fmamk_f32 v5, v5, 0x3b800000, v251
	v_cmp_gt_f32_e32 vcc, s19, v5
	v_mul_f32_e32 v6, 0x4f800000, v5
	s_nop 0
	v_cndmask_b32_e32 v5, v5, v6, vcc
	v_sqrt_f32_e32 v6, v5
	s_nop 0
	v_add_u32_e32 v7, -1, v6
	v_fma_f32 v8, -v7, v6, v5
	v_cmp_ge_f32_e64 s[2:3], 0, v8
	v_add_u32_e32 v8, 1, v6
	s_nop 0
	v_cndmask_b32_e64 v7, v6, v7, s[2:3]
	v_fma_f32 v6, -v8, v6, v5
	v_cmp_lt_f32_e64 s[2:3], 0, v6
	s_nop 1
	v_cndmask_b32_e64 v6, v7, v8, s[2:3]
	v_mul_f32_e32 v7, 0x37800000, v6
	v_cndmask_b32_e32 v6, v6, v7, vcc
	v_cmp_class_f32_e32 vcc, v5, v252
	s_nop 1
	v_cndmask_b32_e32 v5, v6, v5, vcc
	v_div_scale_f32 v6, s[2:3], v5, v5, 1.0
	v_rcp_f32_e32 v7, v6
	s_or_b32 s2, s54, s31
	v_or_b32_e32 v212, s2, v161
	v_fma_f32 v8, -v6, v7, 1.0
	v_fmac_f32_e32 v7, v8, v7
	v_div_scale_f32 v8, vcc, 1.0, v5, 1.0
	v_mul_f32_e32 v9, v8, v7
	v_fma_f32 v10, -v6, v9, v8
	v_fmac_f32_e32 v9, v10, v7
	v_fma_f32 v6, -v6, v9, v8
	v_div_fmas_f32 v6, v6, v7, v9
	v_div_fixup_f32 v6, v6, v5, 1.0
	v_pk_mul_f32 v[0:1], v[0:1], v[6:7] op_sel_hi:[1,0]
	s_waitcnt vmcnt(31)
	v_lshlrev_b32_e32 v8, 16, v74
	v_and_b32_e32 v9, 0xffff0000, v74
	v_pk_mul_f32 v[2:3], v[2:3], v[6:7] op_sel_hi:[1,0]
	v_lshlrev_b32_e32 v6, 16, v75
	v_and_b32_e32 v7, 0xffff0000, v75
	v_pk_mul_f32 v[0:1], v[0:1], v[8:9]
	v_pk_mul_f32 v[2:3], v[2:3], v[6:7]
	v_cvt_pk_bf16_f32 v0, v0, v1
	v_cvt_pk_bf16_f32 v1, v2, v3
	v_lshl_add_u64 v[2:3], v[212:213], 1, s[6:7]
	global_store_dwordx2 v[2:3], v[0:1], off
	v_add_u32_e32 v0, s37, v4
	ds_read_b128 v[0:3], v0
	s_waitcnt lgkmcnt(0)
	v_mov_b32_e32 v6, v1
	v_mov_b32_e32 v7, v2
	v_mov_b32_e32 v8, v0
	v_mov_b32_e32 v9, v3
	v_pk_add_f32 v[6:7], v[6:7], v[8:9]
	s_nop 0
	v_add_f32_e32 v5, v6, v7
	s_nop 1
	v_add_f32_dpp v5, v5, v5 quad_perm:[1,0,3,2] row_mask:0xf bank_mask:0xf
	s_nop 1
	v_add_f32_dpp v5, v5, v5 quad_perm:[2,3,0,1] row_mask:0xf bank_mask:0xf
	s_nop 1
	v_add_f32_dpp v5, v5, v5 row_half_mirror row_mask:0xf bank_mask:0xf
	s_nop 1
	v_add_f32_dpp v5, v5, v5 row_mirror row_mask:0xf bank_mask:0xf
	v_mov_b32_e32 v6, v5
	s_nop 1
	v_permlane16_swap_b32_e32 v5, v6
	v_add_f32_e32 v5, v5, v6
	v_mov_b32_e32 v6, v5
	s_nop 1
	v_permlane32_swap_b32_e32 v5, v6
	v_add_f32_e32 v5, v5, v6
	v_fmamk_f32 v1, v5, 0xbb800000, v1
	v_fmamk_f32 v0, v5, 0xbb800000, v0
	v_fmamk_f32 v3, v5, 0xbb800000, v3
	v_fmac_f32_e32 v2, 0xbb800000, v5
	v_pk_mul_f32 v[6:7], v[2:3], v[2:3]
	v_pk_mul_f32 v[8:9], v[0:1], v[0:1]
	s_nop 0
	v_pk_mov_b32 v[10:11], v[8:9], v[6:7] op_sel:[1,0]
	v_mov_b32_e32 v9, v7
	v_pk_add_f32 v[6:7], v[10:11], v[8:9]
	s_nop 0
	v_add_f32_e32 v5, v6, v7
	s_nop 1
	v_add_f32_dpp v5, v5, v5 quad_perm:[1,0,3,2] row_mask:0xf bank_mask:0xf
	s_nop 1
	v_add_f32_dpp v5, v5, v5 quad_perm:[2,3,0,1] row_mask:0xf bank_mask:0xf
	s_nop 1
	v_add_f32_dpp v5, v5, v5 row_half_mirror row_mask:0xf bank_mask:0xf
	s_nop 1
	v_add_f32_dpp v5, v5, v5 row_mirror row_mask:0xf bank_mask:0xf
	v_mov_b32_e32 v6, v5
	s_nop 1
	v_permlane16_swap_b32_e32 v5, v6
	v_add_f32_e32 v5, v5, v6
	v_mov_b32_e32 v6, v5
	s_nop 1
	v_permlane32_swap_b32_e32 v5, v6
	v_add_f32_e32 v5, v5, v6
	v_fmamk_f32 v5, v5, 0x3b800000, v251
	v_cmp_gt_f32_e32 vcc, s19, v5
	v_mul_f32_e32 v6, 0x4f800000, v5
	s_nop 0
	v_cndmask_b32_e32 v5, v5, v6, vcc
	v_sqrt_f32_e32 v6, v5
	s_nop 0
	v_add_u32_e32 v7, -1, v6
	v_fma_f32 v8, -v7, v6, v5
	v_cmp_ge_f32_e64 s[2:3], 0, v8
	v_add_u32_e32 v8, 1, v6
	s_nop 0
	v_cndmask_b32_e64 v7, v6, v7, s[2:3]
	v_fma_f32 v6, -v8, v6, v5
	v_cmp_lt_f32_e64 s[2:3], 0, v6
	s_nop 1
	v_cndmask_b32_e64 v6, v7, v8, s[2:3]
	v_mul_f32_e32 v7, 0x37800000, v6
	v_cndmask_b32_e32 v6, v6, v7, vcc
	v_cmp_class_f32_e32 vcc, v5, v252
	s_nop 1
	v_cndmask_b32_e32 v5, v6, v5, vcc
	v_div_scale_f32 v6, s[2:3], v5, v5, 1.0
	v_rcp_f32_e32 v7, v6
	s_or_b32 s2, s54, s38
	v_or_b32_e32 v212, s2, v161
	v_fma_f32 v8, -v6, v7, 1.0
	v_fmac_f32_e32 v7, v8, v7
	v_div_scale_f32 v8, vcc, 1.0, v5, 1.0
	v_mul_f32_e32 v9, v8, v7
	v_fma_f32 v10, -v6, v9, v8
	v_fmac_f32_e32 v9, v10, v7
	v_fma_f32 v6, -v6, v9, v8
	v_div_fmas_f32 v6, v6, v7, v9
	v_div_fixup_f32 v6, v6, v5, 1.0
	v_pk_mul_f32 v[0:1], v[0:1], v[6:7] op_sel_hi:[1,0]
	s_waitcnt vmcnt(31)
	v_lshlrev_b32_e32 v8, 16, v72
	v_and_b32_e32 v9, 0xffff0000, v72
	v_pk_mul_f32 v[2:3], v[2:3], v[6:7] op_sel_hi:[1,0]
	v_lshlrev_b32_e32 v6, 16, v73
	v_and_b32_e32 v7, 0xffff0000, v73
	v_pk_mul_f32 v[0:1], v[0:1], v[8:9]
	v_pk_mul_f32 v[2:3], v[2:3], v[6:7]
	v_cvt_pk_bf16_f32 v0, v0, v1
	v_cvt_pk_bf16_f32 v1, v2, v3
	v_lshl_add_u64 v[2:3], v[212:213], 1, s[6:7]
	global_store_dwordx2 v[2:3], v[0:1], off
	v_add_u32_e32 v0, s40, v4
	ds_read_b128 v[0:3], v0
	s_waitcnt lgkmcnt(0)
	v_mov_b32_e32 v6, v1
	v_mov_b32_e32 v7, v2
	v_mov_b32_e32 v8, v0
	v_mov_b32_e32 v9, v3
	v_pk_add_f32 v[6:7], v[6:7], v[8:9]
	s_nop 0
	v_add_f32_e32 v5, v6, v7
	s_nop 1
	v_add_f32_dpp v5, v5, v5 quad_perm:[1,0,3,2] row_mask:0xf bank_mask:0xf
	s_nop 1
	v_add_f32_dpp v5, v5, v5 quad_perm:[2,3,0,1] row_mask:0xf bank_mask:0xf
	s_nop 1
	v_add_f32_dpp v5, v5, v5 row_half_mirror row_mask:0xf bank_mask:0xf
	s_nop 1
	v_add_f32_dpp v5, v5, v5 row_mirror row_mask:0xf bank_mask:0xf
	v_mov_b32_e32 v6, v5
	s_nop 1
	v_permlane16_swap_b32_e32 v5, v6
	v_add_f32_e32 v5, v5, v6
	v_mov_b32_e32 v6, v5
	s_nop 1
	v_permlane32_swap_b32_e32 v5, v6
	v_add_f32_e32 v5, v5, v6
	v_fmamk_f32 v1, v5, 0xbb800000, v1
	v_fmamk_f32 v0, v5, 0xbb800000, v0
	v_fmamk_f32 v3, v5, 0xbb800000, v3
	v_fmac_f32_e32 v2, 0xbb800000, v5
	v_pk_mul_f32 v[6:7], v[2:3], v[2:3]
	v_pk_mul_f32 v[8:9], v[0:1], v[0:1]
	s_nop 0
	v_pk_mov_b32 v[10:11], v[8:9], v[6:7] op_sel:[1,0]
	v_mov_b32_e32 v9, v7
	v_pk_add_f32 v[6:7], v[10:11], v[8:9]
	s_nop 0
	v_add_f32_e32 v5, v6, v7
	s_nop 1
	v_add_f32_dpp v5, v5, v5 quad_perm:[1,0,3,2] row_mask:0xf bank_mask:0xf
	s_nop 1
	v_add_f32_dpp v5, v5, v5 quad_perm:[2,3,0,1] row_mask:0xf bank_mask:0xf
	s_nop 1
	v_add_f32_dpp v5, v5, v5 row_half_mirror row_mask:0xf bank_mask:0xf
	s_nop 1
	v_add_f32_dpp v5, v5, v5 row_mirror row_mask:0xf bank_mask:0xf
	v_mov_b32_e32 v6, v5
	s_nop 1
	v_permlane16_swap_b32_e32 v5, v6
	v_add_f32_e32 v5, v5, v6
	v_mov_b32_e32 v6, v5
	s_nop 1
	v_permlane32_swap_b32_e32 v5, v6
	v_add_f32_e32 v5, v5, v6
	v_fmamk_f32 v5, v5, 0x3b800000, v251
	v_cmp_gt_f32_e32 vcc, s19, v5
	v_mul_f32_e32 v6, 0x4f800000, v5
	s_nop 0
	v_cndmask_b32_e32 v5, v5, v6, vcc
	v_sqrt_f32_e32 v6, v5
	s_nop 0
	v_add_u32_e32 v7, -1, v6
	v_fma_f32 v8, -v7, v6, v5
	v_cmp_ge_f32_e64 s[2:3], 0, v8
	v_add_u32_e32 v8, 1, v6
	s_nop 0
	v_cndmask_b32_e64 v7, v6, v7, s[2:3]
	v_fma_f32 v6, -v8, v6, v5
	v_cmp_lt_f32_e64 s[2:3], 0, v6
	s_nop 1
	v_cndmask_b32_e64 v6, v7, v8, s[2:3]
	v_mul_f32_e32 v7, 0x37800000, v6
	v_cndmask_b32_e32 v6, v6, v7, vcc
	v_cmp_class_f32_e32 vcc, v5, v252
	s_nop 1
	v_cndmask_b32_e32 v5, v6, v5, vcc
	v_div_scale_f32 v6, s[2:3], v5, v5, 1.0
	v_rcp_f32_e32 v7, v6
	s_or_b32 s2, s54, s41
	v_or_b32_e32 v212, s2, v161
	v_fma_f32 v8, -v6, v7, 1.0
	v_fmac_f32_e32 v7, v8, v7
	v_div_scale_f32 v8, vcc, 1.0, v5, 1.0
	v_mul_f32_e32 v9, v8, v7
	v_fma_f32 v10, -v6, v9, v8
	v_fmac_f32_e32 v9, v10, v7
	v_fma_f32 v6, -v6, v9, v8
	v_div_fmas_f32 v6, v6, v7, v9
	v_div_fixup_f32 v6, v6, v5, 1.0
	v_pk_mul_f32 v[0:1], v[0:1], v[6:7] op_sel_hi:[1,0]
	s_waitcnt vmcnt(31)
	v_lshlrev_b32_e32 v8, 16, v70
	v_and_b32_e32 v9, 0xffff0000, v70
	v_pk_mul_f32 v[2:3], v[2:3], v[6:7] op_sel_hi:[1,0]
	v_lshlrev_b32_e32 v6, 16, v71
	v_and_b32_e32 v7, 0xffff0000, v71
	v_pk_mul_f32 v[0:1], v[0:1], v[8:9]
	v_pk_mul_f32 v[2:3], v[2:3], v[6:7]
	v_cvt_pk_bf16_f32 v0, v0, v1
	v_cvt_pk_bf16_f32 v1, v2, v3
	v_lshl_add_u64 v[2:3], v[212:213], 1, s[6:7]
	global_store_dwordx2 v[2:3], v[0:1], off
	v_add_u32_e32 v0, s48, v4
	ds_read_b128 v[0:3], v0
	s_waitcnt lgkmcnt(0)
	v_mov_b32_e32 v6, v1
	v_mov_b32_e32 v7, v2
	v_mov_b32_e32 v8, v0
	v_mov_b32_e32 v9, v3
	v_pk_add_f32 v[6:7], v[6:7], v[8:9]
	s_nop 0
	v_add_f32_e32 v5, v6, v7
	s_nop 1
	v_add_f32_dpp v5, v5, v5 quad_perm:[1,0,3,2] row_mask:0xf bank_mask:0xf
	s_nop 1
	v_add_f32_dpp v5, v5, v5 quad_perm:[2,3,0,1] row_mask:0xf bank_mask:0xf
	s_nop 1
	v_add_f32_dpp v5, v5, v5 row_half_mirror row_mask:0xf bank_mask:0xf
	s_nop 1
	v_add_f32_dpp v5, v5, v5 row_mirror row_mask:0xf bank_mask:0xf
	v_mov_b32_e32 v6, v5
	s_nop 1
	v_permlane16_swap_b32_e32 v5, v6
	v_add_f32_e32 v5, v5, v6
	v_mov_b32_e32 v6, v5
	s_nop 1
	v_permlane32_swap_b32_e32 v5, v6
	v_add_f32_e32 v5, v5, v6
	v_fmamk_f32 v1, v5, 0xbb800000, v1
	v_fmamk_f32 v0, v5, 0xbb800000, v0
	v_fmamk_f32 v3, v5, 0xbb800000, v3
	v_fmac_f32_e32 v2, 0xbb800000, v5
	v_pk_mul_f32 v[6:7], v[2:3], v[2:3]
	v_pk_mul_f32 v[8:9], v[0:1], v[0:1]
	s_nop 0
	v_pk_mov_b32 v[10:11], v[8:9], v[6:7] op_sel:[1,0]
	v_mov_b32_e32 v9, v7
	v_pk_add_f32 v[6:7], v[10:11], v[8:9]
	s_nop 0
	v_add_f32_e32 v5, v6, v7
	s_nop 1
	v_add_f32_dpp v5, v5, v5 quad_perm:[1,0,3,2] row_mask:0xf bank_mask:0xf
	s_nop 1
	v_add_f32_dpp v5, v5, v5 quad_perm:[2,3,0,1] row_mask:0xf bank_mask:0xf
	s_nop 1
	v_add_f32_dpp v5, v5, v5 row_half_mirror row_mask:0xf bank_mask:0xf
	s_nop 1
	v_add_f32_dpp v5, v5, v5 row_mirror row_mask:0xf bank_mask:0xf
	v_mov_b32_e32 v6, v5
	s_nop 1
	v_permlane16_swap_b32_e32 v5, v6
	v_add_f32_e32 v5, v5, v6
	v_mov_b32_e32 v6, v5
	s_nop 1
	v_permlane32_swap_b32_e32 v5, v6
	v_add_f32_e32 v5, v5, v6
	v_fmamk_f32 v5, v5, 0x3b800000, v251
	v_cmp_gt_f32_e32 vcc, s19, v5
	v_mul_f32_e32 v6, 0x4f800000, v5
	s_nop 0
	v_cndmask_b32_e32 v5, v5, v6, vcc
	v_sqrt_f32_e32 v6, v5
	s_nop 0
	v_add_u32_e32 v7, -1, v6
	v_fma_f32 v8, -v7, v6, v5
	v_cmp_ge_f32_e64 s[2:3], 0, v8
	v_add_u32_e32 v8, 1, v6
	s_nop 0
	v_cndmask_b32_e64 v7, v6, v7, s[2:3]
	v_fma_f32 v6, -v8, v6, v5
	v_cmp_lt_f32_e64 s[2:3], 0, v6
	s_nop 1
	v_cndmask_b32_e64 v6, v7, v8, s[2:3]
	v_mul_f32_e32 v7, 0x37800000, v6
	v_cndmask_b32_e32 v6, v6, v7, vcc
	v_cmp_class_f32_e32 vcc, v5, v252
	s_nop 1
	v_cndmask_b32_e32 v5, v6, v5, vcc
	v_div_scale_f32 v6, s[2:3], v5, v5, 1.0
	v_rcp_f32_e32 v7, v6
	s_or_b32 s2, s54, s49
	v_or_b32_e32 v212, s2, v161
	v_fma_f32 v8, -v6, v7, 1.0
	v_fmac_f32_e32 v7, v8, v7
	v_div_scale_f32 v8, vcc, 1.0, v5, 1.0
	v_mul_f32_e32 v9, v8, v7
	v_fma_f32 v10, -v6, v9, v8
	v_fmac_f32_e32 v9, v10, v7
	v_fma_f32 v6, -v6, v9, v8
	v_div_fmas_f32 v6, v6, v7, v9
	v_div_fixup_f32 v6, v6, v5, 1.0
	v_pk_mul_f32 v[0:1], v[0:1], v[6:7] op_sel_hi:[1,0]
	s_waitcnt vmcnt(31)
	v_lshlrev_b32_e32 v8, 16, v68
	v_and_b32_e32 v9, 0xffff0000, v68
	v_pk_mul_f32 v[2:3], v[2:3], v[6:7] op_sel_hi:[1,0]
	v_lshlrev_b32_e32 v6, 16, v69
	v_and_b32_e32 v7, 0xffff0000, v69
	v_pk_mul_f32 v[0:1], v[0:1], v[8:9]
	v_pk_mul_f32 v[2:3], v[2:3], v[6:7]
	v_cvt_pk_bf16_f32 v0, v0, v1
	v_cvt_pk_bf16_f32 v1, v2, v3
	v_lshl_add_u64 v[2:3], v[212:213], 1, s[6:7]
	global_store_dwordx2 v[2:3], v[0:1], off
	v_add_u32_e32 v0, s50, v4
	ds_read_b128 v[0:3], v0
	s_waitcnt lgkmcnt(0)
	v_mov_b32_e32 v6, v1
	v_mov_b32_e32 v7, v2
	v_mov_b32_e32 v8, v0
	v_mov_b32_e32 v9, v3
	v_pk_add_f32 v[6:7], v[6:7], v[8:9]
	s_nop 0
	v_add_f32_e32 v5, v6, v7
	s_nop 1
	v_add_f32_dpp v5, v5, v5 quad_perm:[1,0,3,2] row_mask:0xf bank_mask:0xf
	s_nop 1
	v_add_f32_dpp v5, v5, v5 quad_perm:[2,3,0,1] row_mask:0xf bank_mask:0xf
	s_nop 1
	v_add_f32_dpp v5, v5, v5 row_half_mirror row_mask:0xf bank_mask:0xf
	s_nop 1
	v_add_f32_dpp v5, v5, v5 row_mirror row_mask:0xf bank_mask:0xf
	v_mov_b32_e32 v6, v5
	s_nop 1
	v_permlane16_swap_b32_e32 v5, v6
	v_add_f32_e32 v5, v5, v6
	v_mov_b32_e32 v6, v5
	s_nop 1
	v_permlane32_swap_b32_e32 v5, v6
	v_add_f32_e32 v5, v5, v6
	v_fmamk_f32 v1, v5, 0xbb800000, v1
	v_fmamk_f32 v0, v5, 0xbb800000, v0
	v_fmamk_f32 v3, v5, 0xbb800000, v3
	v_fmac_f32_e32 v2, 0xbb800000, v5
	v_pk_mul_f32 v[6:7], v[2:3], v[2:3]
	v_pk_mul_f32 v[8:9], v[0:1], v[0:1]
	s_nop 0
	v_pk_mov_b32 v[10:11], v[8:9], v[6:7] op_sel:[1,0]
	v_mov_b32_e32 v9, v7
	v_pk_add_f32 v[6:7], v[10:11], v[8:9]
	s_nop 0
	v_add_f32_e32 v5, v6, v7
	s_nop 1
	v_add_f32_dpp v5, v5, v5 quad_perm:[1,0,3,2] row_mask:0xf bank_mask:0xf
	s_nop 1
	v_add_f32_dpp v5, v5, v5 quad_perm:[2,3,0,1] row_mask:0xf bank_mask:0xf
	s_nop 1
	v_add_f32_dpp v5, v5, v5 row_half_mirror row_mask:0xf bank_mask:0xf
	s_nop 1
	v_add_f32_dpp v5, v5, v5 row_mirror row_mask:0xf bank_mask:0xf
	v_mov_b32_e32 v6, v5
	s_nop 1
	v_permlane16_swap_b32_e32 v5, v6
	v_add_f32_e32 v5, v5, v6
	v_mov_b32_e32 v6, v5
	s_nop 1
	v_permlane32_swap_b32_e32 v5, v6
	v_add_f32_e32 v5, v5, v6
	v_fmamk_f32 v5, v5, 0x3b800000, v251
	v_cmp_gt_f32_e32 vcc, s19, v5
	v_mul_f32_e32 v6, 0x4f800000, v5
	s_nop 0
	v_cndmask_b32_e32 v5, v5, v6, vcc
	v_sqrt_f32_e32 v6, v5
	s_nop 0
	v_add_u32_e32 v7, -1, v6
	v_fma_f32 v8, -v7, v6, v5
	v_cmp_ge_f32_e64 s[2:3], 0, v8
	v_add_u32_e32 v8, 1, v6
	s_nop 0
	v_cndmask_b32_e64 v7, v6, v7, s[2:3]
	v_fma_f32 v6, -v8, v6, v5
	v_cmp_lt_f32_e64 s[2:3], 0, v6
	s_nop 1
	v_cndmask_b32_e64 v6, v7, v8, s[2:3]
	v_mul_f32_e32 v7, 0x37800000, v6
	v_cndmask_b32_e32 v6, v6, v7, vcc
	v_cmp_class_f32_e32 vcc, v5, v252
	s_nop 1
	v_cndmask_b32_e32 v5, v6, v5, vcc
	v_div_scale_f32 v6, s[2:3], v5, v5, 1.0
	v_rcp_f32_e32 v7, v6
	s_or_b32 s2, s54, s51
	v_or_b32_e32 v212, s2, v161
	v_fma_f32 v8, -v6, v7, 1.0
	v_fmac_f32_e32 v7, v8, v7
	v_div_scale_f32 v8, vcc, 1.0, v5, 1.0
	v_mul_f32_e32 v9, v8, v7
	v_fma_f32 v10, -v6, v9, v8
	v_fmac_f32_e32 v9, v10, v7
	v_fma_f32 v6, -v6, v9, v8
	v_div_fmas_f32 v6, v6, v7, v9
	v_div_fixup_f32 v6, v6, v5, 1.0
	v_pk_mul_f32 v[0:1], v[0:1], v[6:7] op_sel_hi:[1,0]
	s_waitcnt vmcnt(31)
	v_lshlrev_b32_e32 v8, 16, v66
	v_and_b32_e32 v9, 0xffff0000, v66
	v_pk_mul_f32 v[2:3], v[2:3], v[6:7] op_sel_hi:[1,0]
	v_lshlrev_b32_e32 v6, 16, v67
	v_and_b32_e32 v7, 0xffff0000, v67
	v_pk_mul_f32 v[0:1], v[0:1], v[8:9]
	v_pk_mul_f32 v[2:3], v[2:3], v[6:7]
	v_cvt_pk_bf16_f32 v0, v0, v1
	v_cvt_pk_bf16_f32 v1, v2, v3
	v_lshl_add_u64 v[2:3], v[212:213], 1, s[6:7]
	global_store_dwordx2 v[2:3], v[0:1], off
	v_add_u32_e32 v0, s52, v4
	ds_read_b128 v[0:3], v0
	s_waitcnt lgkmcnt(0)
	v_mov_b32_e32 v4, v1
	v_mov_b32_e32 v5, v2
	v_mov_b32_e32 v6, v0
	v_mov_b32_e32 v7, v3
	v_pk_add_f32 v[4:5], v[4:5], v[6:7]
	s_nop 0
	v_add_f32_e32 v4, v4, v5
	s_nop 1
	v_add_f32_dpp v4, v4, v4 quad_perm:[1,0,3,2] row_mask:0xf bank_mask:0xf
	s_nop 1
	v_add_f32_dpp v4, v4, v4 quad_perm:[2,3,0,1] row_mask:0xf bank_mask:0xf
	s_nop 1
	v_add_f32_dpp v4, v4, v4 row_half_mirror row_mask:0xf bank_mask:0xf
	s_nop 1
	v_add_f32_dpp v4, v4, v4 row_mirror row_mask:0xf bank_mask:0xf
	v_mov_b32_e32 v5, v4
	s_nop 1
	v_permlane16_swap_b32_e32 v4, v5
	v_add_f32_e32 v4, v4, v5
	v_mov_b32_e32 v5, v4
	s_nop 1
	v_permlane32_swap_b32_e32 v4, v5
	v_add_f32_e32 v4, v4, v5
	v_fmamk_f32 v1, v4, 0xbb800000, v1
	v_fmamk_f32 v0, v4, 0xbb800000, v0
	v_fmamk_f32 v3, v4, 0xbb800000, v3
	v_fmac_f32_e32 v2, 0xbb800000, v4
	v_pk_mul_f32 v[4:5], v[2:3], v[2:3]
	v_pk_mul_f32 v[6:7], v[0:1], v[0:1]
	s_nop 0
	v_pk_mov_b32 v[8:9], v[6:7], v[4:5] op_sel:[1,0]
	v_mov_b32_e32 v7, v5
	v_pk_add_f32 v[4:5], v[8:9], v[6:7]
	s_nop 0
	v_add_f32_e32 v4, v4, v5
	s_nop 1
	v_add_f32_dpp v4, v4, v4 quad_perm:[1,0,3,2] row_mask:0xf bank_mask:0xf
	s_nop 1
	v_add_f32_dpp v4, v4, v4 quad_perm:[2,3,0,1] row_mask:0xf bank_mask:0xf
	s_nop 1
	v_add_f32_dpp v4, v4, v4 row_half_mirror row_mask:0xf bank_mask:0xf
	s_nop 1
	v_add_f32_dpp v4, v4, v4 row_mirror row_mask:0xf bank_mask:0xf
	v_mov_b32_e32 v5, v4
	s_nop 1
	v_permlane16_swap_b32_e32 v4, v5
	v_add_f32_e32 v4, v4, v5
	v_mov_b32_e32 v5, v4
	s_nop 1
	v_permlane32_swap_b32_e32 v4, v5
	v_add_f32_e32 v4, v4, v5
	v_fmamk_f32 v4, v4, 0x3b800000, v251
	v_cmp_gt_f32_e32 vcc, s19, v4
	v_mul_f32_e32 v5, 0x4f800000, v4
	s_nop 0
	v_cndmask_b32_e32 v4, v4, v5, vcc
	v_sqrt_f32_e32 v5, v4
	s_nop 0
	v_add_u32_e32 v6, -1, v5
	v_fma_f32 v7, -v6, v5, v4
	v_cmp_ge_f32_e64 s[2:3], 0, v7
	v_add_u32_e32 v7, 1, v5
	s_nop 0
	v_cndmask_b32_e64 v6, v5, v6, s[2:3]
	v_fma_f32 v5, -v7, v5, v4
	v_cmp_lt_f32_e64 s[2:3], 0, v5
	s_nop 1
	v_cndmask_b32_e64 v5, v6, v7, s[2:3]
	v_mul_f32_e32 v6, 0x37800000, v5
	v_cndmask_b32_e32 v5, v5, v6, vcc
	v_cmp_class_f32_e32 vcc, v4, v252
	s_nop 1
	v_cndmask_b32_e32 v4, v5, v4, vcc
	v_div_scale_f32 v5, s[2:3], v4, v4, 1.0
	v_rcp_f32_e32 v6, v5
	s_or_b32 s2, s54, s53
	v_or_b32_e32 v212, s2, v161
	v_fma_f32 v7, -v5, v6, 1.0
	v_fmac_f32_e32 v6, v7, v6
	v_div_scale_f32 v7, vcc, 1.0, v4, 1.0
	v_mul_f32_e32 v8, v7, v6
	v_fma_f32 v9, -v5, v8, v7
	v_fmac_f32_e32 v8, v9, v6
	v_fma_f32 v5, -v5, v8, v7
	v_div_fmas_f32 v5, v5, v6, v8
	v_div_fixup_f32 v4, v5, v4, 1.0
	v_pk_mul_f32 v[0:1], v[0:1], v[4:5] op_sel_hi:[1,0]
	s_waitcnt vmcnt(31)
	v_lshlrev_b32_e32 v6, 16, v64
	v_and_b32_e32 v7, 0xffff0000, v64
	v_pk_mul_f32 v[2:3], v[2:3], v[4:5] op_sel_hi:[1,0]
	v_lshlrev_b32_e32 v4, 16, v65
	v_and_b32_e32 v5, 0xffff0000, v65
	v_pk_mul_f32 v[0:1], v[0:1], v[6:7]
	v_pk_mul_f32 v[2:3], v[2:3], v[4:5]
	v_cvt_pk_bf16_f32 v0, v0, v1
	v_cvt_pk_bf16_f32 v1, v2, v3
	v_lshl_add_u64 v[2:3], v[212:213], 1, s[6:7]
	global_store_dwordx2 v[2:3], v[0:1], off
	s_andn2_b64 vcc, exec, s[4:5]
	s_cbranch_vccz .LBB0_663

.Lrc_lastunit:
	s_waitcnt vmcnt(0)
	s_branch .LBB0_637
